# dattn unit epilogue: the 16 sub-layer gain loads hoisted to the epilogue start, counted vmcnt instead of 8 serialized load-wait-store round trips
# speedup vs baseline: 1.0043x; 1.0043x over previous
; __device__ __forceinline__ int crow(int r, int hi) { return (r & 3) + 8 * (r >> 2) + 4 * hi; }
; __device__ __forceinline__ void dattn_unit(const Args& a, unsigned char* ws, LAS unsigned char* lds, int l, int unit, int tid, int wid, int lane, int dry) {
;     ...
;         const float inv = 1.f / lsum; float ssq = 0.f;
; #pragma unroll
;         for (int eb = 0; eb < 4; ++eb)
; #pragma unroll
;             for (int r = 0; r < 16; ++r) { const float o = O[eb][r] * inv - Y[(32 * eb + crow(r, hi)) * 32 + r32]; O[eb][r] = o; ssq += o * o; }
;         ssq += __shfl_xor(ssq, 32);
;         const float rs = __builtin_amdgcn_rsqf(ssq * (1.f / 128.f) + EPS) * oneml;
;         const float* sg = a.in[13] + l * 128;
;         bf16* op = P + tok * NIN + 2048 + h * 128;
; #pragma unroll
;         for (int eb = 0; eb < 4; ++eb)
; #pragma unroll
;             for (int pr = 0; pr < 2; ++pr) {
;                 u32x2 wa, wb;
;                 { const int rq = 2 * pr, e0 = 32 * eb + 8 * rq + 4 * hi; const f32x4 gv = *(const f32x4*)(sg + e0);
.LBB0_661:
	v_div_scale_f32 v65, s[10:11], v64, v64, 1.0
	v_rcp_f32_e32 v66, v65
	v_div_scale_f32 v68, vcc, 1.0, v64, 1.0
	v_fma_f32 v69, -v65, v66, 1.0
	v_fmac_f32_e32 v66, v69, v66
	v_mul_f32_e32 v69, v68, v66
	v_fma_f32 v70, -v65, v69, v68
	v_fmac_f32_e32 v69, v70, v66
	v_fma_f32 v65, -v65, v69, v68
	v_div_fmas_f32 v65, v65, v66, v69
	v_div_fixup_f32 v66, v65, v64, 1.0
	v_lshlrev_b32_e32 v64, 9, v202
	v_lshlrev_b32_e32 v65, 2, v203
	v_add3_u32 v68, s36, v64, v65
	v_add_u32_e32 v64, 0x400, v68
	ds_read2_b32 v[76:77], v68 offset1:32
	ds_read2_b32 v[78:79], v68 offset0:64 offset1:96
	ds_read2_b32 v[80:81], v64 offset1:32
	ds_read2_b32 v[82:83], v64 offset0:64 offset1:96
	v_add_u32_e32 v64, 0x800, v68
	ds_read2_b32 v[84:85], v64 offset1:32
	ds_read2_b32 v[86:87], v64 offset0:64 offset1:96
	v_add_u32_e32 v64, 0xc00, v68
	ds_read2_b32 v[88:89], v64 offset1:32
	ds_read2_b32 v[90:91], v64 offset0:64 offset1:96
	v_add_u32_e32 v64, 0x1000, v68
	ds_read2_b32 v[92:93], v64 offset1:32
	ds_read2_b32 v[94:95], v64 offset0:64 offset1:96
	v_add_u32_e32 v64, 0x1400, v68
	ds_read2_b32 v[96:97], v64 offset1:32
	ds_read2_b32 v[98:99], v64 offset0:64 offset1:96
	v_add_u32_e32 v64, 0x1800, v68
	ds_read2_b32 v[100:101], v64 offset1:32
	ds_read2_b32 v[102:103], v64 offset0:64 offset1:96
	v_add_u32_e32 v64, 0x1c00, v68
	ds_read2_b32 v[104:105], v64 offset1:32
	ds_read2_b32 v[106:107], v64 offset0:64 offset1:96
	v_add_u32_e32 v64, 0x2000, v68
	ds_read2_b32 v[108:109], v64 offset1:32
	ds_read2_b32 v[110:111], v64 offset0:64 offset1:96
	v_add_u32_e32 v64, 0x2400, v68
	ds_read2_b32 v[112:113], v64 offset1:32
	ds_read2_b32 v[114:115], v64 offset0:64 offset1:96
	v_add_u32_e32 v64, 0x2800, v68
	ds_read2_b32 v[116:117], v64 offset1:32
	ds_read2_b32 v[118:119], v64 offset0:64 offset1:96
	v_add_u32_e32 v64, 0x2c00, v68
	ds_read2_b32 v[120:121], v64 offset1:32
	ds_read2_b32 v[122:123], v64 offset0:64 offset1:96
	v_add_u32_e32 v64, 0x3000, v68
	ds_read2_b32 v[124:125], v64 offset1:32
	ds_read2_b32 v[126:127], v64 offset0:64 offset1:96
	v_add_u32_e32 v64, 0x3400, v68
	v_add_u32_e32 v70, 0x3800, v68
	ds_read2_b32 v[128:129], v64 offset1:32
	ds_read2_b32 v[130:131], v64 offset0:64 offset1:96
	ds_read2_b32 v[64:65], v70 offset0:64 offset1:96
	v_add_u32_e32 v71, 0x3c00, v68
	ds_read2_b32 v[68:69], v71 offset1:32
	ds_read2_b32 v[132:133], v70 offset1:32
	ds_read2_b32 v[70:71], v71 offset0:64 offset1:96
	s_waitcnt lgkmcnt(14)
	v_pk_fma_f32 v[76:77], v[48:49], v[66:67], v[76:77] op_sel_hi:[1,0,1] neg_lo:[0,0,1] neg_hi:[0,0,1]
	v_pk_fma_f32 v[78:79], v[50:51], v[66:67], v[78:79] op_sel_hi:[1,0,1] neg_lo:[0,0,1] neg_hi:[0,0,1]
	s_waitcnt lgkmcnt(3)
	v_pk_fma_f32 v[10:11], v[10:11], v[66:67], v[64:65] op_sel_hi:[1,0,1] neg_lo:[0,0,1] neg_hi:[0,0,1]
	v_lshlrev_b32_e32 v64, 2, v202
	v_ashrrev_i32_e32 v65, 31, v64
	v_lshl_add_u64 v[64:65], v[64:65], 2, s[20:21]
	s_waitcnt lgkmcnt(2)
	v_pk_fma_f32 v[12:13], v[12:13], v[66:67], v[68:69] op_sel_hi:[1,0,1] neg_lo:[0,0,1] neg_hi:[0,0,1]
	s_waitcnt lgkmcnt(0)
	v_pk_fma_f32 v[14:15], v[14:15], v[66:67], v[70:71] op_sel_hi:[1,0,1] neg_lo:[0,0,1] neg_hi:[0,0,1]
	global_load_dwordx4 v[68:71], v[64:65], off
	global_load_dwordx4 v[72:75], v[64:65], off offset:32
	global_load_dwordx4 v[148:151], v[64:65], off offset:64
	global_load_dwordx4 v[152:155], v[64:65], off offset:96
	global_load_dwordx4 v[156:159], v[64:65], off offset:128
	global_load_dwordx4 v[160:163], v[64:65], off offset:160
	global_load_dwordx4 v[164:167], v[64:65], off offset:192
	global_load_dwordx4 v[168:171], v[64:65], off offset:224
	global_load_dwordx4 v[172:175], v[64:65], off offset:256
	global_load_dwordx4 v[184:187], v[64:65], off offset:288
	global_load_dwordx4 v[188:191], v[64:65], off offset:320
	global_load_dwordx4 v[192:195], v[64:65], off offset:352
	global_load_dwordx4 v[204:207], v[64:65], off offset:384
	global_load_dwordx4 v[208:211], v[64:65], off offset:416
	global_load_dwordx4 v[212:215], v[64:65], off offset:448
	global_load_dwordx4 v[216:219], v[64:65], off offset:480
	v_pk_mul_f32 v[140:141], v[76:77], v[76:77]
	v_pk_fma_f32 v[54:55], v[54:55], v[66:67], v[82:83] op_sel_hi:[1,0,1] neg_lo:[0,0,1] neg_hi:[0,0,1]
	v_pk_fma_f32 v[52:53], v[52:53], v[66:67], v[80:81] op_sel_hi:[1,0,1] neg_lo:[0,0,1] neg_hi:[0,0,1]
	v_pk_mul_f32 v[50:51], v[78:79], v[78:79]
	v_pk_fma_f32 v[62:63], v[62:63], v[66:67], v[90:91] op_sel_hi:[1,0,1] neg_lo:[0,0,1] neg_hi:[0,0,1]
	v_pk_fma_f32 v[60:61], v[60:61], v[66:67], v[88:89] op_sel_hi:[1,0,1] neg_lo:[0,0,1] neg_hi:[0,0,1]
	v_pk_fma_f32 v[58:59], v[58:59], v[66:67], v[86:87] op_sel_hi:[1,0,1] neg_lo:[0,0,1] neg_hi:[0,0,1]
	v_pk_fma_f32 v[84:85], v[56:57], v[66:67], v[84:85] op_sel_hi:[1,0,1] neg_lo:[0,0,1] neg_hi:[0,0,1]
	v_pk_fma_f32 v[48:49], v[38:39], v[66:67], v[98:99] op_sel_hi:[1,0,1] neg_lo:[0,0,1] neg_hi:[0,0,1]
	v_pk_fma_f32 v[96:97], v[36:37], v[66:67], v[96:97] op_sel_hi:[1,0,1] neg_lo:[0,0,1] neg_hi:[0,0,1]
	v_pk_fma_f32 v[94:95], v[34:35], v[66:67], v[94:95] op_sel_hi:[1,0,1] neg_lo:[0,0,1] neg_hi:[0,0,1]
	v_pk_fma_f32 v[92:93], v[32:33], v[66:67], v[92:93] op_sel_hi:[1,0,1] neg_lo:[0,0,1] neg_hi:[0,0,1]
	v_pk_fma_f32 v[34:35], v[46:47], v[66:67], v[106:107] op_sel_hi:[1,0,1] neg_lo:[0,0,1] neg_hi:[0,0,1]
	v_pk_fma_f32 v[44:45], v[44:45], v[66:67], v[104:105] op_sel_hi:[1,0,1] neg_lo:[0,0,1] neg_hi:[0,0,1]
	v_pk_fma_f32 v[42:43], v[42:43], v[66:67], v[102:103] op_sel_hi:[1,0,1] neg_lo:[0,0,1] neg_hi:[0,0,1]
	v_pk_fma_f32 v[40:41], v[40:41], v[66:67], v[100:101] op_sel_hi:[1,0,1] neg_lo:[0,0,1] neg_hi:[0,0,1]
	v_pk_fma_f32 v[22:23], v[22:23], v[66:67], v[114:115] op_sel_hi:[1,0,1] neg_lo:[0,0,1] neg_hi:[0,0,1]
; __device__ __forceinline__ unsigned pkbf(float lo, float hi) { typedef __bf16 bf2_t __attribute__((ext_vector_type(2))); f32x2 v = {lo, hi}; bf2_t b = __builtin_convertvector(v, bf2_t); return __builtin_bit_cast(unsigned, b); }
; __device__ __forceinline__ int crow(int r, int hi) { return (r & 3) + 8 * (r >> 2) + 4 * hi; }
; __device__ __forceinline__ void dattn_unit(const Args& a, unsigned char* ws, LAS unsigned char* lds, int l, int unit, int tid, int wid, int lane, int dry) {
;     ...
; #pragma unroll
;             for (int r = 0; r < 16; ++r) { const float o = O[eb][r] * inv - Y[(32 * eb + crow(r, hi)) * 32 + r32]; O[eb][r] = o; ssq += o * o; }
;         ssq += __shfl_xor(ssq, 32);
;         const float rs = __builtin_amdgcn_rsqf(ssq * (1.f / 128.f) + EPS) * oneml;
;         const float* sg = a.in[13] + l * 128;
;         bf16* op = P + tok * NIN + 2048 + h * 128;
; #pragma unroll
;         for (int eb = 0; eb < 4; ++eb)
; #pragma unroll
;             for (int pr = 0; pr < 2; ++pr) {
;                 u32x2 wa, wb;
;                 { const int rq = 2 * pr, e0 = 32 * eb + 8 * rq + 4 * hi; const f32x4 gv = *(const f32x4*)(sg + e0);
;                   wa.x = pkbf(O[eb][4 * rq] * rs * gv[0], O[eb][4 * rq + 1] * rs * gv[1]); wa.y = pkbf(O[eb][4 * rq + 2] * rs * gv[2], O[eb][4 * rq + 3] * rs * gv[3]); }
;                 { const int rq = 2 * pr + 1, e0 = 32 * eb + 8 * rq + 4 * hi; const f32x4 gv = *(const f32x4*)(sg + e0);
;                   wb.x = pkbf(O[eb][4 * rq] * rs * gv[0], O[eb][4 * rq + 1] * rs * gv[1]); wb.y = pkbf(O[eb][4 * rq + 2] * rs * gv[2], O[eb][4 * rq + 3] * rs * gv[3]); }
	v_pk_fma_f32 v[32:33], v[20:21], v[66:67], v[112:113] op_sel_hi:[1,0,1] neg_lo:[0,0,1] neg_hi:[0,0,1]
	v_pk_fma_f32 v[36:37], v[18:19], v[66:67], v[110:111] op_sel_hi:[1,0,1] neg_lo:[0,0,1] neg_hi:[0,0,1]
	v_pk_fma_f32 v[38:39], v[16:17], v[66:67], v[108:109] op_sel_hi:[1,0,1] neg_lo:[0,0,1] neg_hi:[0,0,1]
	v_pk_fma_f32 v[16:17], v[30:31], v[66:67], v[122:123] op_sel_hi:[1,0,1] neg_lo:[0,0,1] neg_hi:[0,0,1]
	v_pk_fma_f32 v[20:21], v[28:29], v[66:67], v[120:121] op_sel_hi:[1,0,1] neg_lo:[0,0,1] neg_hi:[0,0,1]
	v_pk_fma_f32 v[26:27], v[26:27], v[66:67], v[118:119] op_sel_hi:[1,0,1] neg_lo:[0,0,1] neg_hi:[0,0,1]
	v_pk_fma_f32 v[24:25], v[24:25], v[66:67], v[116:117] op_sel_hi:[1,0,1] neg_lo:[0,0,1] neg_hi:[0,0,1]
	v_pk_fma_f32 v[6:7], v[6:7], v[66:67], v[130:131] op_sel_hi:[1,0,1] neg_lo:[0,0,1] neg_hi:[0,0,1]
	v_pk_fma_f32 v[4:5], v[4:5], v[66:67], v[128:129] op_sel_hi:[1,0,1] neg_lo:[0,0,1] neg_hi:[0,0,1]
	v_pk_fma_f32 v[2:3], v[2:3], v[66:67], v[126:127] op_sel_hi:[1,0,1] neg_lo:[0,0,1] neg_hi:[0,0,1]
	v_pk_fma_f32 v[18:19], v[0:1], v[66:67], v[124:125] op_sel_hi:[1,0,1] neg_lo:[0,0,1] neg_hi:[0,0,1]
	v_pk_fma_f32 v[0:1], v[8:9], v[66:67], v[132:133] op_sel_hi:[1,0,1] neg_lo:[0,0,1] neg_hi:[0,0,1]
	v_add_f32_e32 v66, v140, v141
	v_add_f32_e32 v50, v66, v50
	v_pk_mul_f32 v[80:81], v[52:53], v[52:53]
	v_add_f32_e32 v50, v50, v51
	v_add_f32_e32 v50, v50, v80
	v_pk_mul_f32 v[82:83], v[54:55], v[54:55]
	v_add_f32_e32 v50, v50, v81
	v_add_f32_e32 v50, v50, v82
	v_pk_mul_f32 v[56:57], v[84:85], v[84:85]
	v_add_f32_e32 v50, v50, v83
	v_add_f32_e32 v50, v50, v56
	v_pk_mul_f32 v[86:87], v[58:59], v[58:59]
	v_add_f32_e32 v50, v50, v57
	v_add_f32_e32 v50, v50, v86
	v_pk_mul_f32 v[88:89], v[60:61], v[60:61]
	v_add_f32_e32 v50, v50, v87
	v_add_f32_e32 v50, v50, v88
	v_pk_mul_f32 v[90:91], v[62:63], v[62:63]
	v_add_f32_e32 v50, v50, v89
	v_add_f32_e32 v50, v50, v90
	v_pk_mul_f32 v[146:147], v[92:93], v[92:93]
	v_add_f32_e32 v50, v50, v91
	v_add_f32_e32 v50, v50, v146
	v_pk_mul_f32 v[144:145], v[94:95], v[94:95]
	v_add_f32_e32 v50, v50, v147
	v_add_f32_e32 v50, v50, v144
	v_pk_mul_f32 v[142:143], v[96:97], v[96:97]
	v_add_f32_e32 v50, v50, v145
	v_add_f32_e32 v50, v50, v142
	v_pk_mul_f32 v[98:99], v[48:49], v[48:49]
	v_add_f32_e32 v50, v50, v143
	v_add_f32_e32 v50, v50, v98
	v_pk_mul_f32 v[100:101], v[40:41], v[40:41]
	v_add_f32_e32 v50, v50, v99
	v_add_f32_e32 v50, v50, v100
	v_pk_mul_f32 v[102:103], v[42:43], v[42:43]
	v_add_f32_e32 v50, v50, v101
	v_add_f32_e32 v50, v50, v102
	v_pk_mul_f32 v[104:105], v[44:45], v[44:45]
	v_add_f32_e32 v50, v50, v103
	v_add_f32_e32 v50, v50, v104
	v_pk_mul_f32 v[46:47], v[34:35], v[34:35]
	v_add_f32_e32 v50, v50, v105
	v_add_f32_e32 v46, v50, v46
	v_pk_mul_f32 v[108:109], v[38:39], v[38:39]
	v_add_f32_e32 v46, v46, v47
	v_add_f32_e32 v46, v46, v108
	v_pk_mul_f32 v[110:111], v[36:37], v[36:37]
	v_add_f32_e32 v46, v46, v109
	v_add_f32_e32 v46, v46, v110
	v_pk_mul_f32 v[112:113], v[32:33], v[32:33]
	v_add_f32_e32 v46, v46, v111
	v_add_f32_e32 v46, v46, v112
	v_pk_mul_f32 v[106:107], v[22:23], v[22:23]
	v_add_f32_e32 v46, v46, v113
	v_add_f32_e32 v46, v46, v106
	v_pk_mul_f32 v[116:117], v[24:25], v[24:25]
	v_add_f32_e32 v46, v46, v107
	v_add_f32_e32 v46, v46, v116
	v_pk_mul_f32 v[114:115], v[26:27], v[26:27]
	v_add_f32_e32 v46, v46, v117
	v_add_f32_e32 v46, v46, v114
	v_pk_mul_f32 v[28:29], v[20:21], v[20:21]
	v_add_f32_e32 v46, v46, v115
	v_add_f32_e32 v28, v46, v28
	v_pk_mul_f32 v[30:31], v[16:17], v[16:17]
	v_add_f32_e32 v28, v28, v29
	v_add_f32_e32 v28, v28, v30
	v_pk_mul_f32 v[124:125], v[18:19], v[18:19]
	v_add_f32_e32 v28, v28, v31
	v_add_f32_e32 v28, v28, v124
	v_pk_mul_f32 v[122:123], v[2:3], v[2:3]
	v_add_f32_e32 v28, v28, v125
	v_add_f32_e32 v28, v28, v122
	v_pk_mul_f32 v[120:121], v[4:5], v[4:5]
	v_add_f32_e32 v28, v28, v123
	v_add_f32_e32 v28, v28, v120
	v_pk_mul_f32 v[118:119], v[6:7], v[6:7]
	v_add_f32_e32 v28, v28, v121
	v_add_f32_e32 v28, v28, v118
	v_pk_mul_f32 v[8:9], v[0:1], v[0:1]
	v_add_f32_e32 v28, v28, v119
	v_add_f32_e32 v8, v28, v8
	v_pk_mul_f32 v[134:135], v[10:11], v[10:11]
	v_add_f32_e32 v8, v8, v9
	v_add_f32_e32 v8, v8, v134
	v_pk_mul_f32 v[136:137], v[12:13], v[12:13]
	v_add_f32_e32 v8, v8, v135
	v_add_f32_e32 v8, v8, v136
	v_pk_mul_f32 v[138:139], v[14:15], v[14:15]
	v_add_f32_e32 v8, v8, v137
	v_add_f32_e32 v8, v8, v138
	v_add_f32_e32 v8, v8, v139
	ds_bpermute_b32 v9, v200, v8
	s_waitcnt lgkmcnt(0)
	v_add_f32_e32 v8, v8, v9
	v_fmamk_f32 v8, v8, 0x3c000000, v201
	v_rsq_f32_e32 v28, v8
	v_lshl_add_u64 v[8:9], v[182:183], 1, v[180:181]
	v_mul_f32_e32 v28, v67, v28
	v_pk_mul_f32 v[30:31], v[76:77], v[28:29] op_sel_hi:[1,0]
	v_pk_mul_f32 v[46:47], v[94:95], v[28:29] op_sel_hi:[1,0]
	s_waitcnt vmcnt(15)
	v_pk_mul_f32 v[30:31], v[68:69], v[30:31]
	v_pk_mul_f32 v[48:49], v[48:49], v[28:29] op_sel_hi:[1,0]
	v_cvt_pk_bf16_f32 v50, v30, v31
	v_pk_mul_f32 v[30:31], v[78:79], v[28:29] op_sel_hi:[1,0]
	v_pk_mul_f32 v[34:35], v[34:35], v[28:29] op_sel_hi:[1,0]
	v_pk_mul_f32 v[30:31], v[70:71], v[30:31]
	v_pk_mul_f32 v[32:33], v[32:33], v[28:29] op_sel_hi:[1,0]
	v_cvt_pk_bf16_f32 v51, v30, v31
	v_pk_mul_f32 v[30:31], v[52:53], v[28:29] op_sel_hi:[1,0]
	v_pk_mul_f32 v[22:23], v[22:23], v[28:29] op_sel_hi:[1,0]
	s_waitcnt vmcnt(14)
; __device__ __forceinline__ unsigned pkbf(float lo, float hi) { typedef __bf16 bf2_t __attribute__((ext_vector_type(2))); f32x2 v = {lo, hi}; bf2_t b = __builtin_convertvector(v, bf2_t); return __builtin_bit_cast(unsigned, b); }
; __device__ __forceinline__ void dattn_unit(const Args& a, unsigned char* ws, LAS unsigned char* lds, int l, int unit, int tid, int wid, int lane, int dry) {
;     ...
;             for (int pr = 0; pr < 2; ++pr) {
;                 u32x2 wa, wb;
;                 { const int rq = 2 * pr, e0 = 32 * eb + 8 * rq + 4 * hi; const f32x4 gv = *(const f32x4*)(sg + e0);
;                   wa.x = pkbf(O[eb][4 * rq] * rs * gv[0], O[eb][4 * rq + 1] * rs * gv[1]); wa.y = pkbf(O[eb][4 * rq + 2] * rs * gv[2], O[eb][4 * rq + 3] * rs * gv[3]); }
;                 { const int rq = 2 * pr + 1, e0 = 32 * eb + 8 * rq + 4 * hi; const f32x4 gv = *(const f32x4*)(sg + e0);
;                   wb.x = pkbf(O[eb][4 * rq] * rs * gv[0], O[eb][4 * rq + 1] * rs * gv[1]); wb.y = pkbf(O[eb][4 * rq + 2] * rs * gv[2], O[eb][4 * rq + 3] * rs * gv[3]); }
;                 const auto sx = __builtin_amdgcn_permlane32_swap(wa.x, wb.x, false, false), sy = __builtin_amdgcn_permlane32_swap(wa.y, wb.y, false, false);
;                 u32x4 w; w.x = sx[0]; w.y = sy[0]; w.z = sx[1]; w.w = sy[1];
;                 *(u32x4*)(op + 32 * eb + 16 * pr + 8 * hi) = w;
;             }
	v_pk_mul_f32 v[30:31], v[72:73], v[30:31]
	v_pk_mul_f32 v[20:21], v[20:21], v[28:29] op_sel_hi:[1,0]
	v_cvt_pk_bf16_f32 v52, v30, v31
	v_pk_mul_f32 v[30:31], v[54:55], v[28:29] op_sel_hi:[1,0]
	s_nop 0
	v_permlane32_swap_b32_e32 v50, v52
	v_pk_mul_f32 v[30:31], v[74:75], v[30:31]
	v_pk_mul_f32 v[16:17], v[16:17], v[28:29] op_sel_hi:[1,0]
	v_cvt_pk_bf16_f32 v53, v30, v31
	s_nop 1
	v_permlane32_swap_b32_e32 v51, v53
	global_store_dwordx4 v[8:9], v[50:53], off
	s_nop 0
	s_nop 0
	s_nop 0
	v_pk_mul_f32 v[30:31], v[84:85], v[28:29] op_sel_hi:[1,0]
	v_pk_mul_f32 v[2:3], v[2:3], v[28:29] op_sel_hi:[1,0]
	v_pk_mul_f32 v[4:5], v[4:5], v[28:29] op_sel_hi:[1,0]
	v_pk_mul_f32 v[6:7], v[6:7], v[28:29] op_sel_hi:[1,0]
	v_pk_mul_f32 v[0:1], v[0:1], v[28:29] op_sel_hi:[1,0]
	s_waitcnt vmcnt(13)
	v_pk_mul_f32 v[30:31], v[148:149], v[30:31]
	s_nop 0
	v_cvt_pk_bf16_f32 v50, v30, v31
	v_pk_mul_f32 v[30:31], v[58:59], v[28:29] op_sel_hi:[1,0]
	v_pk_mul_f32 v[58:59], v[96:97], v[28:29] op_sel_hi:[1,0]
	v_pk_mul_f32 v[30:31], v[150:151], v[30:31]
	s_nop 0
	v_cvt_pk_bf16_f32 v51, v30, v31
	v_pk_mul_f32 v[30:31], v[60:61], v[28:29] op_sel_hi:[1,0]
	s_waitcnt vmcnt(12)
	v_pk_mul_f32 v[30:31], v[30:31], v[152:153]
	s_nop 0
	v_cvt_pk_bf16_f32 v52, v30, v31
	v_pk_mul_f32 v[30:31], v[62:63], v[28:29] op_sel_hi:[1,0]
	s_nop 0
	v_permlane32_swap_b32_e32 v50, v52
	v_pk_mul_f32 v[30:31], v[30:31], v[154:155]
	s_nop 0
	v_cvt_pk_bf16_f32 v53, v30, v31
	s_nop 1
	v_permlane32_swap_b32_e32 v51, v53
	global_store_dwordx4 v[8:9], v[50:53], off offset:32
	s_nop 0
	s_nop 0
	s_nop 0
	v_pk_mul_f32 v[30:31], v[92:93], v[28:29] op_sel_hi:[1,0]
	s_waitcnt vmcnt(11)
	v_pk_mul_f32 v[30:31], v[30:31], v[156:157]
	v_pk_mul_f32 v[50:51], v[46:47], v[158:159]
	s_waitcnt vmcnt(10)
	v_pk_mul_f32 v[52:53], v[58:59], v[160:161]
	v_pk_mul_f32 v[54:55], v[48:49], v[162:163]
	v_cvt_pk_bf16_f32 v46, v30, v31
	v_cvt_pk_bf16_f32 v47, v50, v51
	v_cvt_pk_bf16_f32 v48, v52, v53
	v_cvt_pk_bf16_f32 v49, v54, v55
	s_nop 0
	v_permlane32_swap_b32_e32 v46, v48
	v_permlane32_swap_b32_e32 v47, v49
	global_store_dwordx4 v[8:9], v[46:49], off offset:64
	s_nop 0
	s_nop 0
	s_nop 0
	v_pk_mul_f32 v[30:31], v[40:41], v[28:29] op_sel_hi:[1,0]
	v_pk_mul_f32 v[40:41], v[42:43], v[28:29] op_sel_hi:[1,0]
	v_pk_mul_f32 v[42:43], v[44:45], v[28:29] op_sel_hi:[1,0]
	s_waitcnt vmcnt(9)
	v_pk_mul_f32 v[30:31], v[30:31], v[164:165]
	v_pk_mul_f32 v[44:45], v[40:41], v[166:167]
	s_waitcnt vmcnt(8)
	v_pk_mul_f32 v[42:43], v[42:43], v[168:169]
	v_pk_mul_f32 v[34:35], v[34:35], v[170:171]
	v_cvt_pk_bf16_f32 v40, v30, v31
	v_cvt_pk_bf16_f32 v41, v44, v45
	v_cvt_pk_bf16_f32 v42, v42, v43
	v_cvt_pk_bf16_f32 v43, v34, v35
	s_nop 0
	v_permlane32_swap_b32_e32 v40, v42
	v_permlane32_swap_b32_e32 v41, v43
	global_store_dwordx4 v[8:9], v[40:43], off offset:96
	s_nop 0
	s_nop 0
	s_nop 0
	v_pk_mul_f32 v[30:31], v[38:39], v[28:29] op_sel_hi:[1,0]
	v_pk_mul_f32 v[34:35], v[36:37], v[28:29] op_sel_hi:[1,0]
	s_waitcnt vmcnt(7)
	v_pk_mul_f32 v[30:31], v[30:31], v[172:173]
	v_pk_mul_f32 v[34:35], v[34:35], v[174:175]
	s_waitcnt vmcnt(6)
	v_pk_mul_f32 v[32:33], v[32:33], v[184:185]
	v_pk_mul_f32 v[22:23], v[22:23], v[186:187]
	v_cvt_pk_bf16_f32 v30, v30, v31
	v_cvt_pk_bf16_f32 v31, v34, v35
	v_cvt_pk_bf16_f32 v32, v32, v33
	v_cvt_pk_bf16_f32 v33, v22, v23
	s_nop 0
	v_permlane32_swap_b32_e32 v30, v32
	v_permlane32_swap_b32_e32 v31, v33
	global_store_dwordx4 v[8:9], v[30:33], off offset:128
	s_nop 0
	s_nop 0
	s_nop 0
	v_pk_mul_f32 v[22:23], v[24:25], v[28:29] op_sel_hi:[1,0]
	v_pk_mul_f32 v[24:25], v[26:27], v[28:29] op_sel_hi:[1,0]
	s_waitcnt vmcnt(5)
	v_pk_mul_f32 v[22:23], v[22:23], v[188:189]
	v_pk_mul_f32 v[24:25], v[24:25], v[190:191]
	s_waitcnt vmcnt(4)
	v_pk_mul_f32 v[26:27], v[20:21], v[192:193]
	v_pk_mul_f32 v[16:17], v[16:17], v[194:195]
	v_cvt_pk_bf16_f32 v20, v22, v23
	v_cvt_pk_bf16_f32 v21, v24, v25
	v_cvt_pk_bf16_f32 v22, v26, v27
	v_cvt_pk_bf16_f32 v23, v16, v17
	s_nop 0
	v_permlane32_swap_b32_e32 v20, v22
	v_permlane32_swap_b32_e32 v21, v23
	global_store_dwordx4 v[8:9], v[20:23], off offset:160
	s_nop 0
	s_nop 0
	s_nop 0
	v_pk_mul_f32 v[16:17], v[18:19], v[28:29] op_sel_hi:[1,0]
	s_waitcnt vmcnt(3)
	v_pk_mul_f32 v[18:19], v[2:3], v[206:207]
	v_pk_mul_f32 v[16:17], v[16:17], v[204:205]
	s_waitcnt vmcnt(2)
	v_pk_mul_f32 v[4:5], v[4:5], v[208:209]
	v_pk_mul_f32 v[6:7], v[6:7], v[210:211]
	v_cvt_pk_bf16_f32 v2, v16, v17
	v_cvt_pk_bf16_f32 v3, v18, v19
	v_cvt_pk_bf16_f32 v4, v4, v5
	v_cvt_pk_bf16_f32 v5, v6, v7
	s_nop 0
	v_permlane32_swap_b32_e32 v2, v4
	v_permlane32_swap_b32_e32 v3, v5
	global_store_dwordx4 v[8:9], v[2:5], off offset:192
	s_nop 0
	s_nop 0
	s_nop 0
	v_pk_mul_f32 v[6:7], v[10:11], v[28:29] op_sel_hi:[1,0]
	v_pk_mul_f32 v[10:11], v[12:13], v[28:29] op_sel_hi:[1,0]
	v_pk_mul_f32 v[12:13], v[14:15], v[28:29] op_sel_hi:[1,0]
	s_waitcnt vmcnt(1)
	v_pk_mul_f32 v[0:1], v[0:1], v[212:213]
	v_pk_mul_f32 v[2:3], v[6:7], v[214:215]
	s_waitcnt vmcnt(0)
	v_pk_mul_f32 v[4:5], v[10:11], v[216:217]
	v_pk_mul_f32 v[6:7], v[12:13], v[218:219]
	v_cvt_pk_bf16_f32 v0, v0, v1
	v_cvt_pk_bf16_f32 v1, v2, v3
	v_cvt_pk_bf16_f32 v2, v4, v5
	v_cvt_pk_bf16_f32 v3, v6, v7
	s_nop 0
	v_permlane32_swap_b32_e32 v0, v2
	v_permlane32_swap_b32_e32 v1, v3
	global_store_dwordx4 v[8:9], v[0:3], off offset:224
	s_branch .LBB0_639

; __device__ __forceinline__ int crow(int r, int hi) { return (r & 3) + 8 * (r >> 2) + 4 * hi; }
; __device__ __forceinline__ void dattn_unit(const Args& a, unsigned char* ws, LAS unsigned char* lds, int l, int unit, int tid, int wid, int lane, int dry) {
;     ...
;         const float inv = 1.f / lsum; float ssq = 0.f;
; #pragma unroll
;         for (int eb = 0; eb < 4; ++eb)
; #pragma unroll
;             for (int r = 0; r < 16; ++r) { const float o = O[eb][r] * inv - Y[(32 * eb + crow(r, hi)) * 32 + r32]; O[eb][r] = o; ssq += o * o; }
;         ssq += __shfl_xor(ssq, 32);
;         const float rs = __builtin_amdgcn_rsqf(ssq * (1.f / 128.f) + EPS) * oneml;
;         const float* sg = a.in[13] + l * 128;
;         bf16* op = P + tok * NIN + 2048 + h * 128;
; #pragma unroll
;         for (int eb = 0; eb < 4; ++eb)
; #pragma unroll
;             for (int pr = 0; pr < 2; ++pr) {
;                 u32x2 wa, wb;
;                 { const int rq = 2 * pr, e0 = 32 * eb + 8 * rq + 4 * hi; const f32x4 gv = *(const f32x4*)(sg + e0);
.LBB0_1389:
	v_div_scale_f32 v65, s[10:11], v64, v64, 1.0
	v_rcp_f32_e32 v66, v65
	v_div_scale_f32 v68, vcc, 1.0, v64, 1.0
	v_fma_f32 v69, -v65, v66, 1.0
	v_fmac_f32_e32 v66, v69, v66
	v_mul_f32_e32 v69, v68, v66
	v_fma_f32 v70, -v65, v69, v68
	v_fmac_f32_e32 v69, v70, v66
	v_fma_f32 v65, -v65, v69, v68
	v_div_fmas_f32 v65, v65, v66, v69
	v_div_fixup_f32 v66, v65, v64, 1.0
	v_lshlrev_b32_e32 v64, 9, v202
	v_lshlrev_b32_e32 v65, 2, v203
	v_add3_u32 v68, s36, v64, v65
	v_add_u32_e32 v64, 0x400, v68
	ds_read2_b32 v[76:77], v68 offset1:32
	ds_read2_b32 v[78:79], v68 offset0:64 offset1:96
	ds_read2_b32 v[80:81], v64 offset1:32
	ds_read2_b32 v[82:83], v64 offset0:64 offset1:96
	v_add_u32_e32 v64, 0x800, v68
	ds_read2_b32 v[84:85], v64 offset1:32
	ds_read2_b32 v[86:87], v64 offset0:64 offset1:96
	v_add_u32_e32 v64, 0xc00, v68
	ds_read2_b32 v[88:89], v64 offset1:32
	ds_read2_b32 v[90:91], v64 offset0:64 offset1:96
	v_add_u32_e32 v64, 0x1000, v68
	ds_read2_b32 v[92:93], v64 offset1:32
	ds_read2_b32 v[94:95], v64 offset0:64 offset1:96
	v_add_u32_e32 v64, 0x1400, v68
	ds_read2_b32 v[96:97], v64 offset1:32
	ds_read2_b32 v[98:99], v64 offset0:64 offset1:96
	v_add_u32_e32 v64, 0x1800, v68
	ds_read2_b32 v[100:101], v64 offset1:32
	ds_read2_b32 v[102:103], v64 offset0:64 offset1:96
	v_add_u32_e32 v64, 0x1c00, v68
	ds_read2_b32 v[104:105], v64 offset1:32
	ds_read2_b32 v[106:107], v64 offset0:64 offset1:96
	v_add_u32_e32 v64, 0x2000, v68
	ds_read2_b32 v[108:109], v64 offset1:32
	ds_read2_b32 v[110:111], v64 offset0:64 offset1:96
	v_add_u32_e32 v64, 0x2400, v68
	ds_read2_b32 v[112:113], v64 offset1:32
	ds_read2_b32 v[114:115], v64 offset0:64 offset1:96
	v_add_u32_e32 v64, 0x2800, v68
	ds_read2_b32 v[116:117], v64 offset1:32
	ds_read2_b32 v[118:119], v64 offset0:64 offset1:96
	v_add_u32_e32 v64, 0x2c00, v68
	ds_read2_b32 v[120:121], v64 offset1:32
	ds_read2_b32 v[122:123], v64 offset0:64 offset1:96
	v_add_u32_e32 v64, 0x3000, v68
	ds_read2_b32 v[124:125], v64 offset1:32
	ds_read2_b32 v[126:127], v64 offset0:64 offset1:96
	v_add_u32_e32 v64, 0x3400, v68
	v_add_u32_e32 v70, 0x3800, v68
	ds_read2_b32 v[128:129], v64 offset1:32
	ds_read2_b32 v[130:131], v64 offset0:64 offset1:96
	ds_read2_b32 v[64:65], v70 offset0:64 offset1:96
	v_add_u32_e32 v71, 0x3c00, v68
	ds_read2_b32 v[68:69], v71 offset1:32
	ds_read2_b32 v[132:133], v70 offset1:32
	ds_read2_b32 v[70:71], v71 offset0:64 offset1:96
	s_waitcnt lgkmcnt(14)
	v_pk_fma_f32 v[76:77], v[48:49], v[66:67], v[76:77] op_sel_hi:[1,0,1] neg_lo:[0,0,1] neg_hi:[0,0,1]
	v_pk_fma_f32 v[78:79], v[50:51], v[66:67], v[78:79] op_sel_hi:[1,0,1] neg_lo:[0,0,1] neg_hi:[0,0,1]
	s_waitcnt lgkmcnt(3)
	v_pk_fma_f32 v[10:11], v[10:11], v[66:67], v[64:65] op_sel_hi:[1,0,1] neg_lo:[0,0,1] neg_hi:[0,0,1]
	v_lshlrev_b32_e32 v64, 2, v202
	v_ashrrev_i32_e32 v65, 31, v64
	v_lshl_add_u64 v[64:65], v[64:65], 2, s[20:21]
	s_waitcnt lgkmcnt(2)
	v_pk_fma_f32 v[12:13], v[12:13], v[66:67], v[68:69] op_sel_hi:[1,0,1] neg_lo:[0,0,1] neg_hi:[0,0,1]
	s_waitcnt lgkmcnt(0)
	v_pk_fma_f32 v[14:15], v[14:15], v[66:67], v[70:71] op_sel_hi:[1,0,1] neg_lo:[0,0,1] neg_hi:[0,0,1]
	global_load_dwordx4 v[68:71], v[64:65], off offset:512
	global_load_dwordx4 v[72:75], v[64:65], off offset:544
	global_load_dwordx4 v[148:151], v[64:65], off offset:576
	global_load_dwordx4 v[152:155], v[64:65], off offset:608
	global_load_dwordx4 v[156:159], v[64:65], off offset:640
	global_load_dwordx4 v[160:163], v[64:65], off offset:672
	global_load_dwordx4 v[164:167], v[64:65], off offset:704
	global_load_dwordx4 v[168:171], v[64:65], off offset:736
	global_load_dwordx4 v[172:175], v[64:65], off offset:768
	global_load_dwordx4 v[184:187], v[64:65], off offset:800
	global_load_dwordx4 v[188:191], v[64:65], off offset:832
	global_load_dwordx4 v[192:195], v[64:65], off offset:864
	global_load_dwordx4 v[204:207], v[64:65], off offset:896
	global_load_dwordx4 v[208:211], v[64:65], off offset:928
	global_load_dwordx4 v[212:215], v[64:65], off offset:960
	global_load_dwordx4 v[216:219], v[64:65], off offset:992
	v_pk_mul_f32 v[140:141], v[76:77], v[76:77]
	v_pk_fma_f32 v[54:55], v[54:55], v[66:67], v[82:83] op_sel_hi:[1,0,1] neg_lo:[0,0,1] neg_hi:[0,0,1]
	v_pk_fma_f32 v[52:53], v[52:53], v[66:67], v[80:81] op_sel_hi:[1,0,1] neg_lo:[0,0,1] neg_hi:[0,0,1]
	v_pk_mul_f32 v[50:51], v[78:79], v[78:79]
	v_pk_fma_f32 v[62:63], v[62:63], v[66:67], v[90:91] op_sel_hi:[1,0,1] neg_lo:[0,0,1] neg_hi:[0,0,1]
	v_pk_fma_f32 v[60:61], v[60:61], v[66:67], v[88:89] op_sel_hi:[1,0,1] neg_lo:[0,0,1] neg_hi:[0,0,1]
	v_pk_fma_f32 v[58:59], v[58:59], v[66:67], v[86:87] op_sel_hi:[1,0,1] neg_lo:[0,0,1] neg_hi:[0,0,1]
	v_pk_fma_f32 v[84:85], v[56:57], v[66:67], v[84:85] op_sel_hi:[1,0,1] neg_lo:[0,0,1] neg_hi:[0,0,1]
	v_pk_fma_f32 v[48:49], v[38:39], v[66:67], v[98:99] op_sel_hi:[1,0,1] neg_lo:[0,0,1] neg_hi:[0,0,1]
	v_pk_fma_f32 v[96:97], v[36:37], v[66:67], v[96:97] op_sel_hi:[1,0,1] neg_lo:[0,0,1] neg_hi:[0,0,1]
	v_pk_fma_f32 v[94:95], v[34:35], v[66:67], v[94:95] op_sel_hi:[1,0,1] neg_lo:[0,0,1] neg_hi:[0,0,1]
	v_pk_fma_f32 v[92:93], v[32:33], v[66:67], v[92:93] op_sel_hi:[1,0,1] neg_lo:[0,0,1] neg_hi:[0,0,1]
	v_pk_fma_f32 v[34:35], v[46:47], v[66:67], v[106:107] op_sel_hi:[1,0,1] neg_lo:[0,0,1] neg_hi:[0,0,1]
	v_pk_fma_f32 v[44:45], v[44:45], v[66:67], v[104:105] op_sel_hi:[1,0,1] neg_lo:[0,0,1] neg_hi:[0,0,1]
	v_pk_fma_f32 v[42:43], v[42:43], v[66:67], v[102:103] op_sel_hi:[1,0,1] neg_lo:[0,0,1] neg_hi:[0,0,1]
	v_pk_fma_f32 v[40:41], v[40:41], v[66:67], v[100:101] op_sel_hi:[1,0,1] neg_lo:[0,0,1] neg_hi:[0,0,1]
	v_pk_fma_f32 v[22:23], v[22:23], v[66:67], v[114:115] op_sel_hi:[1,0,1] neg_lo:[0,0,1] neg_hi:[0,0,1]
; __device__ __forceinline__ unsigned pkbf(float lo, float hi) { typedef __bf16 bf2_t __attribute__((ext_vector_type(2))); f32x2 v = {lo, hi}; bf2_t b = __builtin_convertvector(v, bf2_t); return __builtin_bit_cast(unsigned, b); }
; __device__ __forceinline__ int crow(int r, int hi) { return (r & 3) + 8 * (r >> 2) + 4 * hi; }
; __device__ __forceinline__ void dattn_unit(const Args& a, unsigned char* ws, LAS unsigned char* lds, int l, int unit, int tid, int wid, int lane, int dry) {
;     ...
;             for (int r = 0; r < 16; ++r) { const float o = O[eb][r] * inv - Y[(32 * eb + crow(r, hi)) * 32 + r32]; O[eb][r] = o; ssq += o * o; }
;         ssq += __shfl_xor(ssq, 32);
;         const float rs = __builtin_amdgcn_rsqf(ssq * (1.f / 128.f) + EPS) * oneml;
;         const float* sg = a.in[13] + l * 128;
;         bf16* op = P + tok * NIN + 2048 + h * 128;
; #pragma unroll
;         for (int eb = 0; eb < 4; ++eb)
; #pragma unroll
;             for (int pr = 0; pr < 2; ++pr) {
;                 u32x2 wa, wb;
;                 { const int rq = 2 * pr, e0 = 32 * eb + 8 * rq + 4 * hi; const f32x4 gv = *(const f32x4*)(sg + e0);
;                   wa.x = pkbf(O[eb][4 * rq] * rs * gv[0], O[eb][4 * rq + 1] * rs * gv[1]); wa.y = pkbf(O[eb][4 * rq + 2] * rs * gv[2], O[eb][4 * rq + 3] * rs * gv[3]); }
;                 { const int rq = 2 * pr + 1, e0 = 32 * eb + 8 * rq + 4 * hi; const f32x4 gv = *(const f32x4*)(sg + e0);
	v_pk_fma_f32 v[32:33], v[20:21], v[66:67], v[112:113] op_sel_hi:[1,0,1] neg_lo:[0,0,1] neg_hi:[0,0,1]
	v_pk_fma_f32 v[36:37], v[18:19], v[66:67], v[110:111] op_sel_hi:[1,0,1] neg_lo:[0,0,1] neg_hi:[0,0,1]
	v_pk_fma_f32 v[38:39], v[16:17], v[66:67], v[108:109] op_sel_hi:[1,0,1] neg_lo:[0,0,1] neg_hi:[0,0,1]
	v_pk_fma_f32 v[16:17], v[30:31], v[66:67], v[122:123] op_sel_hi:[1,0,1] neg_lo:[0,0,1] neg_hi:[0,0,1]
	v_pk_fma_f32 v[20:21], v[28:29], v[66:67], v[120:121] op_sel_hi:[1,0,1] neg_lo:[0,0,1] neg_hi:[0,0,1]
	v_pk_fma_f32 v[26:27], v[26:27], v[66:67], v[118:119] op_sel_hi:[1,0,1] neg_lo:[0,0,1] neg_hi:[0,0,1]
	v_pk_fma_f32 v[24:25], v[24:25], v[66:67], v[116:117] op_sel_hi:[1,0,1] neg_lo:[0,0,1] neg_hi:[0,0,1]
	v_pk_fma_f32 v[6:7], v[6:7], v[66:67], v[130:131] op_sel_hi:[1,0,1] neg_lo:[0,0,1] neg_hi:[0,0,1]
	v_pk_fma_f32 v[4:5], v[4:5], v[66:67], v[128:129] op_sel_hi:[1,0,1] neg_lo:[0,0,1] neg_hi:[0,0,1]
	v_pk_fma_f32 v[2:3], v[2:3], v[66:67], v[126:127] op_sel_hi:[1,0,1] neg_lo:[0,0,1] neg_hi:[0,0,1]
	v_pk_fma_f32 v[18:19], v[0:1], v[66:67], v[124:125] op_sel_hi:[1,0,1] neg_lo:[0,0,1] neg_hi:[0,0,1]
	v_pk_fma_f32 v[0:1], v[8:9], v[66:67], v[132:133] op_sel_hi:[1,0,1] neg_lo:[0,0,1] neg_hi:[0,0,1]
	v_add_f32_e32 v66, v140, v141
	v_add_f32_e32 v50, v66, v50
	v_pk_mul_f32 v[80:81], v[52:53], v[52:53]
	v_add_f32_e32 v50, v50, v51
	v_add_f32_e32 v50, v50, v80
	v_pk_mul_f32 v[82:83], v[54:55], v[54:55]
	v_add_f32_e32 v50, v50, v81
	v_add_f32_e32 v50, v50, v82
	v_pk_mul_f32 v[56:57], v[84:85], v[84:85]
	v_add_f32_e32 v50, v50, v83
	v_add_f32_e32 v50, v50, v56
	v_pk_mul_f32 v[86:87], v[58:59], v[58:59]
	v_add_f32_e32 v50, v50, v57
	v_add_f32_e32 v50, v50, v86
	v_pk_mul_f32 v[88:89], v[60:61], v[60:61]
	v_add_f32_e32 v50, v50, v87
	v_add_f32_e32 v50, v50, v88
	v_pk_mul_f32 v[90:91], v[62:63], v[62:63]
	v_add_f32_e32 v50, v50, v89
	v_add_f32_e32 v50, v50, v90
	v_pk_mul_f32 v[146:147], v[92:93], v[92:93]
	v_add_f32_e32 v50, v50, v91
	v_add_f32_e32 v50, v50, v146
	v_pk_mul_f32 v[144:145], v[94:95], v[94:95]
	v_add_f32_e32 v50, v50, v147
	v_add_f32_e32 v50, v50, v144
	v_pk_mul_f32 v[142:143], v[96:97], v[96:97]
	v_add_f32_e32 v50, v50, v145
	v_add_f32_e32 v50, v50, v142
	v_pk_mul_f32 v[98:99], v[48:49], v[48:49]
	v_add_f32_e32 v50, v50, v143
	v_add_f32_e32 v50, v50, v98
	v_pk_mul_f32 v[100:101], v[40:41], v[40:41]
	v_add_f32_e32 v50, v50, v99
	v_add_f32_e32 v50, v50, v100
	v_pk_mul_f32 v[102:103], v[42:43], v[42:43]
	v_add_f32_e32 v50, v50, v101
	v_add_f32_e32 v50, v50, v102
	v_pk_mul_f32 v[104:105], v[44:45], v[44:45]
	v_add_f32_e32 v50, v50, v103
	v_add_f32_e32 v50, v50, v104
	v_pk_mul_f32 v[46:47], v[34:35], v[34:35]
	v_add_f32_e32 v50, v50, v105
	v_add_f32_e32 v46, v50, v46
	v_pk_mul_f32 v[108:109], v[38:39], v[38:39]
	v_add_f32_e32 v46, v46, v47
	v_add_f32_e32 v46, v46, v108
	v_pk_mul_f32 v[110:111], v[36:37], v[36:37]
	v_add_f32_e32 v46, v46, v109
	v_add_f32_e32 v46, v46, v110
	v_pk_mul_f32 v[112:113], v[32:33], v[32:33]
	v_add_f32_e32 v46, v46, v111
	v_add_f32_e32 v46, v46, v112
	v_pk_mul_f32 v[106:107], v[22:23], v[22:23]
	v_add_f32_e32 v46, v46, v113
	v_add_f32_e32 v46, v46, v106
	v_pk_mul_f32 v[116:117], v[24:25], v[24:25]
	v_add_f32_e32 v46, v46, v107
	v_add_f32_e32 v46, v46, v116
	v_pk_mul_f32 v[114:115], v[26:27], v[26:27]
	v_add_f32_e32 v46, v46, v117
	v_add_f32_e32 v46, v46, v114
	v_pk_mul_f32 v[28:29], v[20:21], v[20:21]
	v_add_f32_e32 v46, v46, v115
	v_add_f32_e32 v28, v46, v28
	v_pk_mul_f32 v[30:31], v[16:17], v[16:17]
	v_add_f32_e32 v28, v28, v29
	v_add_f32_e32 v28, v28, v30
	v_pk_mul_f32 v[124:125], v[18:19], v[18:19]
	v_add_f32_e32 v28, v28, v31
	v_add_f32_e32 v28, v28, v124
	v_pk_mul_f32 v[122:123], v[2:3], v[2:3]
	v_add_f32_e32 v28, v28, v125
	v_add_f32_e32 v28, v28, v122
	v_pk_mul_f32 v[120:121], v[4:5], v[4:5]
	v_add_f32_e32 v28, v28, v123
	v_add_f32_e32 v28, v28, v120
	v_pk_mul_f32 v[118:119], v[6:7], v[6:7]
	v_add_f32_e32 v28, v28, v121
	v_add_f32_e32 v28, v28, v118
	v_pk_mul_f32 v[8:9], v[0:1], v[0:1]
	v_add_f32_e32 v28, v28, v119
	v_add_f32_e32 v8, v28, v8
	v_pk_mul_f32 v[134:135], v[10:11], v[10:11]
	v_add_f32_e32 v8, v8, v9
	v_add_f32_e32 v8, v8, v134
	v_pk_mul_f32 v[136:137], v[12:13], v[12:13]
	v_add_f32_e32 v8, v8, v135
	v_add_f32_e32 v8, v8, v136
	v_pk_mul_f32 v[138:139], v[14:15], v[14:15]
	v_add_f32_e32 v8, v8, v137
	v_add_f32_e32 v8, v8, v138
	v_add_f32_e32 v8, v8, v139
	ds_bpermute_b32 v9, v200, v8
	s_waitcnt lgkmcnt(0)
	v_add_f32_e32 v8, v8, v9
	v_fmamk_f32 v8, v8, 0x3c000000, v201
	v_rsq_f32_e32 v28, v8
	v_lshl_add_u64 v[8:9], v[182:183], 1, v[180:181]
	v_mul_f32_e32 v28, v67, v28
	v_pk_mul_f32 v[30:31], v[76:77], v[28:29] op_sel_hi:[1,0]
	v_pk_mul_f32 v[46:47], v[94:95], v[28:29] op_sel_hi:[1,0]
	s_waitcnt vmcnt(15)
	v_pk_mul_f32 v[30:31], v[68:69], v[30:31]
	v_pk_mul_f32 v[48:49], v[48:49], v[28:29] op_sel_hi:[1,0]
	v_cvt_pk_bf16_f32 v50, v30, v31
	v_pk_mul_f32 v[30:31], v[78:79], v[28:29] op_sel_hi:[1,0]
	v_pk_mul_f32 v[34:35], v[34:35], v[28:29] op_sel_hi:[1,0]
	v_pk_mul_f32 v[30:31], v[70:71], v[30:31]
	v_pk_mul_f32 v[32:33], v[32:33], v[28:29] op_sel_hi:[1,0]
	v_cvt_pk_bf16_f32 v51, v30, v31
	v_pk_mul_f32 v[30:31], v[52:53], v[28:29] op_sel_hi:[1,0]
	v_pk_mul_f32 v[22:23], v[22:23], v[28:29] op_sel_hi:[1,0]
	s_waitcnt vmcnt(14)
; __device__ __forceinline__ unsigned pkbf(float lo, float hi) { typedef __bf16 bf2_t __attribute__((ext_vector_type(2))); f32x2 v = {lo, hi}; bf2_t b = __builtin_convertvector(v, bf2_t); return __builtin_bit_cast(unsigned, b); }
; __device__ __forceinline__ void dattn_unit(const Args& a, unsigned char* ws, LAS unsigned char* lds, int l, int unit, int tid, int wid, int lane, int dry) {
;     ...
; #pragma unroll
;         for (int eb = 0; eb < 4; ++eb)
; #pragma unroll
;             for (int pr = 0; pr < 2; ++pr) {
;                 u32x2 wa, wb;
;                 { const int rq = 2 * pr, e0 = 32 * eb + 8 * rq + 4 * hi; const f32x4 gv = *(const f32x4*)(sg + e0);
;                   wa.x = pkbf(O[eb][4 * rq] * rs * gv[0], O[eb][4 * rq + 1] * rs * gv[1]); wa.y = pkbf(O[eb][4 * rq + 2] * rs * gv[2], O[eb][4 * rq + 3] * rs * gv[3]); }
;                 { const int rq = 2 * pr + 1, e0 = 32 * eb + 8 * rq + 4 * hi; const f32x4 gv = *(const f32x4*)(sg + e0);
;                   wb.x = pkbf(O[eb][4 * rq] * rs * gv[0], O[eb][4 * rq + 1] * rs * gv[1]); wb.y = pkbf(O[eb][4 * rq + 2] * rs * gv[2], O[eb][4 * rq + 3] * rs * gv[3]); }
;                 const auto sx = __builtin_amdgcn_permlane32_swap(wa.x, wb.x, false, false), sy = __builtin_amdgcn_permlane32_swap(wa.y, wb.y, false, false);
;                 u32x4 w; w.x = sx[0]; w.y = sy[0]; w.z = sx[1]; w.w = sy[1];
;                 *(u32x4*)(op + 32 * eb + 16 * pr + 8 * hi) = w;
	v_pk_mul_f32 v[30:31], v[72:73], v[30:31]
	v_pk_mul_f32 v[20:21], v[20:21], v[28:29] op_sel_hi:[1,0]
	v_cvt_pk_bf16_f32 v52, v30, v31
	v_pk_mul_f32 v[30:31], v[54:55], v[28:29] op_sel_hi:[1,0]
	s_nop 0
	v_permlane32_swap_b32_e32 v50, v52
	v_pk_mul_f32 v[30:31], v[74:75], v[30:31]
	v_pk_mul_f32 v[16:17], v[16:17], v[28:29] op_sel_hi:[1,0]
	v_cvt_pk_bf16_f32 v53, v30, v31
	s_nop 1
	v_permlane32_swap_b32_e32 v51, v53
	global_store_dwordx4 v[8:9], v[50:53], off
	s_nop 0
	s_nop 0
	s_nop 0
	v_pk_mul_f32 v[30:31], v[84:85], v[28:29] op_sel_hi:[1,0]
	v_pk_mul_f32 v[2:3], v[2:3], v[28:29] op_sel_hi:[1,0]
	v_pk_mul_f32 v[4:5], v[4:5], v[28:29] op_sel_hi:[1,0]
	v_pk_mul_f32 v[6:7], v[6:7], v[28:29] op_sel_hi:[1,0]
	v_pk_mul_f32 v[0:1], v[0:1], v[28:29] op_sel_hi:[1,0]
	s_waitcnt vmcnt(13)
	v_pk_mul_f32 v[30:31], v[148:149], v[30:31]
	s_nop 0
	v_cvt_pk_bf16_f32 v50, v30, v31
	v_pk_mul_f32 v[30:31], v[58:59], v[28:29] op_sel_hi:[1,0]
	v_pk_mul_f32 v[58:59], v[96:97], v[28:29] op_sel_hi:[1,0]
	v_pk_mul_f32 v[30:31], v[150:151], v[30:31]
	s_nop 0
	v_cvt_pk_bf16_f32 v51, v30, v31
	v_pk_mul_f32 v[30:31], v[60:61], v[28:29] op_sel_hi:[1,0]
	s_waitcnt vmcnt(12)
	v_pk_mul_f32 v[30:31], v[30:31], v[152:153]
	s_nop 0
	v_cvt_pk_bf16_f32 v52, v30, v31
	v_pk_mul_f32 v[30:31], v[62:63], v[28:29] op_sel_hi:[1,0]
	s_nop 0
	v_permlane32_swap_b32_e32 v50, v52
	v_pk_mul_f32 v[30:31], v[30:31], v[154:155]
	s_nop 0
	v_cvt_pk_bf16_f32 v53, v30, v31
	s_nop 1
	v_permlane32_swap_b32_e32 v51, v53
	global_store_dwordx4 v[8:9], v[50:53], off offset:32
	s_nop 0
	s_nop 0
	s_nop 0
	v_pk_mul_f32 v[30:31], v[92:93], v[28:29] op_sel_hi:[1,0]
	s_waitcnt vmcnt(11)
	v_pk_mul_f32 v[30:31], v[30:31], v[156:157]
	v_pk_mul_f32 v[50:51], v[46:47], v[158:159]
	s_waitcnt vmcnt(10)
	v_pk_mul_f32 v[52:53], v[58:59], v[160:161]
	v_pk_mul_f32 v[54:55], v[48:49], v[162:163]
	v_cvt_pk_bf16_f32 v46, v30, v31
	v_cvt_pk_bf16_f32 v47, v50, v51
	v_cvt_pk_bf16_f32 v48, v52, v53
	v_cvt_pk_bf16_f32 v49, v54, v55
	s_nop 0
	v_permlane32_swap_b32_e32 v46, v48
	v_permlane32_swap_b32_e32 v47, v49
	global_store_dwordx4 v[8:9], v[46:49], off offset:64
	s_nop 0
	s_nop 0
	s_nop 0
	v_pk_mul_f32 v[30:31], v[40:41], v[28:29] op_sel_hi:[1,0]
	v_pk_mul_f32 v[40:41], v[42:43], v[28:29] op_sel_hi:[1,0]
	v_pk_mul_f32 v[42:43], v[44:45], v[28:29] op_sel_hi:[1,0]
	s_waitcnt vmcnt(9)
	v_pk_mul_f32 v[30:31], v[30:31], v[164:165]
	v_pk_mul_f32 v[44:45], v[40:41], v[166:167]
	s_waitcnt vmcnt(8)
	v_pk_mul_f32 v[42:43], v[42:43], v[168:169]
	v_pk_mul_f32 v[34:35], v[34:35], v[170:171]
	v_cvt_pk_bf16_f32 v40, v30, v31
	v_cvt_pk_bf16_f32 v41, v44, v45
	v_cvt_pk_bf16_f32 v42, v42, v43
	v_cvt_pk_bf16_f32 v43, v34, v35
	s_nop 0
	v_permlane32_swap_b32_e32 v40, v42
	v_permlane32_swap_b32_e32 v41, v43
	global_store_dwordx4 v[8:9], v[40:43], off offset:96
	s_nop 0
	s_nop 0
	s_nop 0
	v_pk_mul_f32 v[30:31], v[38:39], v[28:29] op_sel_hi:[1,0]
	v_pk_mul_f32 v[34:35], v[36:37], v[28:29] op_sel_hi:[1,0]
	s_waitcnt vmcnt(7)
	v_pk_mul_f32 v[30:31], v[30:31], v[172:173]
	v_pk_mul_f32 v[34:35], v[34:35], v[174:175]
	s_waitcnt vmcnt(6)
	v_pk_mul_f32 v[32:33], v[32:33], v[184:185]
	v_pk_mul_f32 v[22:23], v[22:23], v[186:187]
	v_cvt_pk_bf16_f32 v30, v30, v31
	v_cvt_pk_bf16_f32 v31, v34, v35
	v_cvt_pk_bf16_f32 v32, v32, v33
	v_cvt_pk_bf16_f32 v33, v22, v23
	s_nop 0
	v_permlane32_swap_b32_e32 v30, v32
	v_permlane32_swap_b32_e32 v31, v33
	global_store_dwordx4 v[8:9], v[30:33], off offset:128
	s_nop 0
	s_nop 0
	s_nop 0
	v_pk_mul_f32 v[22:23], v[24:25], v[28:29] op_sel_hi:[1,0]
	v_pk_mul_f32 v[24:25], v[26:27], v[28:29] op_sel_hi:[1,0]
	s_waitcnt vmcnt(5)
	v_pk_mul_f32 v[22:23], v[22:23], v[188:189]
	v_pk_mul_f32 v[24:25], v[24:25], v[190:191]
	s_waitcnt vmcnt(4)
	v_pk_mul_f32 v[26:27], v[20:21], v[192:193]
	v_pk_mul_f32 v[16:17], v[16:17], v[194:195]
	v_cvt_pk_bf16_f32 v20, v22, v23
	v_cvt_pk_bf16_f32 v21, v24, v25
	v_cvt_pk_bf16_f32 v22, v26, v27
	v_cvt_pk_bf16_f32 v23, v16, v17
	s_nop 0
	v_permlane32_swap_b32_e32 v20, v22
	v_permlane32_swap_b32_e32 v21, v23
	global_store_dwordx4 v[8:9], v[20:23], off offset:160
	s_nop 0
	s_nop 0
	s_nop 0
	v_pk_mul_f32 v[16:17], v[18:19], v[28:29] op_sel_hi:[1,0]
	s_waitcnt vmcnt(3)
	v_pk_mul_f32 v[18:19], v[2:3], v[206:207]
	v_pk_mul_f32 v[16:17], v[16:17], v[204:205]
	s_waitcnt vmcnt(2)
	v_pk_mul_f32 v[4:5], v[4:5], v[208:209]
	v_pk_mul_f32 v[6:7], v[6:7], v[210:211]
	v_cvt_pk_bf16_f32 v2, v16, v17
	v_cvt_pk_bf16_f32 v3, v18, v19
	v_cvt_pk_bf16_f32 v4, v4, v5
	v_cvt_pk_bf16_f32 v5, v6, v7
	s_nop 0
	v_permlane32_swap_b32_e32 v2, v4
	v_permlane32_swap_b32_e32 v3, v5
	global_store_dwordx4 v[8:9], v[2:5], off offset:192
	s_nop 0
	s_nop 0
	s_nop 0
	v_pk_mul_f32 v[6:7], v[10:11], v[28:29] op_sel_hi:[1,0]
	v_pk_mul_f32 v[10:11], v[12:13], v[28:29] op_sel_hi:[1,0]
	v_pk_mul_f32 v[12:13], v[14:15], v[28:29] op_sel_hi:[1,0]
	s_waitcnt vmcnt(1)
	v_pk_mul_f32 v[0:1], v[0:1], v[212:213]
	v_pk_mul_f32 v[2:3], v[6:7], v[214:215]
	s_waitcnt vmcnt(0)
	v_pk_mul_f32 v[4:5], v[10:11], v[216:217]
	v_pk_mul_f32 v[6:7], v[12:13], v[218:219]
	v_cvt_pk_bf16_f32 v0, v0, v1
	v_cvt_pk_bf16_f32 v1, v2, v3
	v_cvt_pk_bf16_f32 v2, v4, v5
	v_cvt_pk_bf16_f32 v3, v6, v7
	s_nop 0
	v_permlane32_swap_b32_e32 v0, v2
	v_permlane32_swap_b32_e32 v1, v3
	global_store_dwordx4 v[8:9], v[0:3], off offset:224
	s_branch .LBB0_1367
